# e8 plus phase-1 RMS-norm row loop: the 12 per-row gamma/scale/shift loads issued together at the row top with counted waits (were 4 serialized groups)
# speedup vs baseline: 1.0094x; 1.0094x over previous
.LBB0_704:
	s_ashr_i32 s3, s6, 13
	v_mad_i64_i32 v[56:57], s[6:7], s3, v252, v[40:41]
	global_load_dwordx4 v[44:47], v[36:37], off
	global_load_dwordx4 v[48:51], v[56:57], off
	v_mad_i64_i32 v[58:59], s[6:7], s3, v252, v[38:39]
	global_load_dwordx4 v[52:55], v[58:59], off
	global_load_dwordx4 v[80:83], v[36:37], off offset:1024
	global_load_dwordx4 v[84:87], v[56:57], off offset:1024
	global_load_dwordx4 v[88:91], v[58:59], off offset:1024
	global_load_dwordx4 v[92:95], v[36:37], off offset:2048
	global_load_dwordx4 v[96:99], v[56:57], off offset:2048
	global_load_dwordx4 v[100:103], v[58:59], off offset:2048
	global_load_dwordx4 v[104:107], v[36:37], off offset:3072
	global_load_dwordx4 v[108:111], v[56:57], off offset:3072
	global_load_dwordx4 v[112:115], v[58:59], off offset:3072
	v_mul_f32_e32 v0, v31, v31
	v_mul_f32_e32 v60, v33, v33
	v_mul_f32_e32 v61, v11, v11
	v_mul_f32_e32 v62, v13, v13
	v_mul_f32_e32 v63, v7, v7
	v_mul_f32_e32 v64, v9, v9
	v_fmac_f32_e32 v0, v30, v30
	v_fmac_f32_e32 v60, v32, v32
	v_fmac_f32_e32 v61, v10, v10
	v_fmac_f32_e32 v62, v12, v12
	v_mul_f32_e32 v65, v3, v3
	v_mul_f32_e32 v66, v5, v5
	v_fmac_f32_e32 v63, v6, v6
	v_fmac_f32_e32 v64, v8, v8
	v_add_f32_e32 v0, v0, v60
	v_add_f32_e32 v60, v61, v62
	v_fmac_f32_e32 v65, v2, v2
	v_fmac_f32_e32 v66, v4, v4
	v_add_f32_e32 v61, v63, v64
	v_add_f32_e32 v0, v0, v60
	v_add_f32_e32 v62, v65, v66
	v_add_f32_e32 v0, v61, v0
	v_add_f32_e32 v0, v62, v0
	ds_swizzle_b32 v60, v0 offset:swizzle(SWAP,1)
	s_and_b64 vcc, exec, s[4:5]
	s_mov_b32 s6, s2
	s_waitcnt lgkmcnt(0)
	v_add_f32_e32 v0, v0, v60
	ds_swizzle_b32 v60, v0 offset:swizzle(SWAP,2)
	s_waitcnt lgkmcnt(0)
	v_add_f32_e32 v0, v0, v60
	ds_swizzle_b32 v60, v0 offset:swizzle(SWAP,4)
	s_waitcnt lgkmcnt(0)
	v_add_f32_e32 v0, v0, v60
	ds_swizzle_b32 v60, v0 offset:swizzle(SWAP,8)
	s_waitcnt lgkmcnt(0)
	v_add_f32_e32 v0, v0, v60
	ds_swizzle_b32 v60, v0 offset:swizzle(SWAP,16)
	s_waitcnt lgkmcnt(0)
	v_add_f32_e32 v0, v0, v60
	v_mov_b32_e32 v60, v0
	s_nop 1
	v_permlane32_swap_b32_e32 v0, v60
	v_add_f32_e32 v0, v0, v60
	v_fmamk_f32 v0, v0, 0x3a800000, v244
	v_rsq_f32_e32 v0, v0
	s_nop 0
	v_pk_mul_f32 v[32:33], v[32:33], v[0:1] op_sel_hi:[1,0]
	v_pk_mul_f32 v[30:31], v[30:31], v[0:1] op_sel_hi:[1,0]
	v_pk_mul_f32 v[12:13], v[12:13], v[0:1] op_sel_hi:[1,0]
	v_pk_mul_f32 v[10:11], v[10:11], v[0:1] op_sel_hi:[1,0]
	v_pk_mul_f32 v[8:9], v[8:9], v[0:1] op_sel_hi:[1,0]
	v_pk_mul_f32 v[6:7], v[6:7], v[0:1] op_sel_hi:[1,0]
	s_waitcnt vmcnt(11)
	v_pk_mul_f32 v[30:31], v[44:45], v[30:31]
	v_pk_mul_f32 v[32:33], v[46:47], v[32:33]
	s_waitcnt vmcnt(10)
	v_pk_add_f32 v[46:47], v[48:49], 1.0 op_sel_hi:[1,0]
	v_pk_add_f32 v[44:45], v[50:51], 1.0 op_sel_hi:[1,0]
	s_waitcnt vmcnt(9)
	v_pk_fma_f32 v[30:31], v[46:47], v[30:31], v[52:53]
	v_pk_fma_f32 v[32:33], v[44:45], v[32:33], v[54:55]
	v_cvt_pk_bf16_f32 v30, v30, v31
	s_nop 0
	v_cvt_pk_bf16_f32 v31, v32, v33
	global_store_dwordx2 v[42:43], v[30:31], off
	s_waitcnt vmcnt(7)
	v_mov_b64_e32 v[30:31], v[80:81]
	v_mov_b64_e32 v[32:33], v[82:83]
	v_mov_b64_e32 v[44:45], v[84:85]
	v_mov_b64_e32 v[46:47], v[86:87]
	v_mov_b64_e32 v[48:49], v[88:89]
	v_mov_b64_e32 v[50:51], v[90:91]
	v_pk_mul_f32 v[10:11], v[30:31], v[10:11]
	v_pk_mul_f32 v[12:13], v[32:33], v[12:13]
	v_pk_add_f32 v[32:33], v[44:45], 1.0 op_sel_hi:[1,0]
	v_pk_add_f32 v[30:31], v[46:47], 1.0 op_sel_hi:[1,0]
	v_pk_fma_f32 v[10:11], v[32:33], v[10:11], v[48:49]
	v_pk_fma_f32 v[12:13], v[30:31], v[12:13], v[50:51]
	v_cvt_pk_bf16_f32 v10, v10, v11
	s_nop 0
	v_cvt_pk_bf16_f32 v11, v12, v13
	global_store_dwordx2 v[42:43], v[10:11], off offset:512
	s_waitcnt vmcnt(5)
	v_mov_b64_e32 v[10:11], v[92:93]
	v_mov_b64_e32 v[12:13], v[94:95]
	v_mov_b64_e32 v[30:31], v[96:97]
	v_mov_b64_e32 v[32:33], v[98:99]
	v_mov_b64_e32 v[44:45], v[100:101]
	v_mov_b64_e32 v[46:47], v[102:103]
	v_pk_mul_f32 v[6:7], v[6:7], v[10:11]
	v_pk_mul_f32 v[8:9], v[8:9], v[12:13]
	v_pk_add_f32 v[12:13], v[30:31], 1.0 op_sel_hi:[1,0]
	v_pk_add_f32 v[10:11], v[32:33], 1.0 op_sel_hi:[1,0]
	v_pk_fma_f32 v[6:7], v[6:7], v[12:13], v[44:45]
	v_pk_fma_f32 v[8:9], v[8:9], v[10:11], v[46:47]
	v_cvt_pk_bf16_f32 v6, v6, v7
	v_mov_b32_e32 v30, v14
	v_cvt_pk_bf16_f32 v7, v8, v9
	global_store_dwordx2 v[42:43], v[6:7], off offset:1024
	s_waitcnt vmcnt(3)
	v_mov_b64_e32 v[44:45], v[104:105]
	v_mov_b64_e32 v[46:47], v[106:107]
	v_mov_b64_e32 v[48:49], v[108:109]
	v_mov_b64_e32 v[50:51], v[110:111]
	v_mov_b64_e32 v[52:53], v[112:113]
	v_mov_b64_e32 v[54:55], v[114:115]
	v_pk_mul_f32 v[58:59], v[2:3], v[0:1] op_sel_hi:[1,0]
	v_pk_mul_f32 v[56:57], v[4:5], v[0:1] op_sel_hi:[1,0]
	v_mov_b32_e32 v31, v15
	v_mov_b32_e32 v12, v20
	v_mov_b32_e32 v13, v21
	v_mov_b32_e32 v32, v16
	v_mov_b32_e32 v33, v17
	v_mov_b32_e32 v10, v18
	v_mov_b32_e32 v11, v19
	v_mov_b32_e32 v6, v22
	v_mov_b32_e32 v7, v23
	v_mov_b32_e32 v8, v24
	v_mov_b32_e32 v9, v25
	v_mov_b32_e32 v2, v26
	v_mov_b32_e32 v3, v27
	v_mov_b32_e32 v4, v28
	v_mov_b32_e32 v5, v29
	v_pk_mul_f32 v[14:15], v[58:59], v[44:45]
	v_pk_add_f32 v[20:21], v[48:49], 1.0 op_sel_hi:[1,0]
	v_pk_mul_f32 v[16:17], v[56:57], v[46:47]
	v_pk_add_f32 v[18:19], v[50:51], 1.0 op_sel_hi:[1,0]
	v_pk_fma_f32 v[14:15], v[14:15], v[20:21], v[52:53]
	v_pk_fma_f32 v[16:17], v[16:17], v[18:19], v[54:55]
	v_cvt_pk_bf16_f32 v14, v14, v15
	s_nop 0
	v_cvt_pk_bf16_f32 v15, v16, v17
	global_store_dwordx2 v[42:43], v[14:15], off offset:1536
	v_lshl_add_u64 v[42:43], v[42:43], 0, s[0:1]
	s_cbranch_vccnz .LBB0_707
